# xconv
# baseline (speedup 1.0000x reference)
; __device__ __forceinline__ void convert_phase(const Params& p, char* shm) {
;     ...
;     for (int i = blockIdx.x * 512 + threadIdx.x; i < n8; i += stride) {
;       float4 v0 = x4[(size_t)i * 2], v1 = x4[(size_t)i * 2 + 1];
;       int row = i >> 8, c = (i & 255) * 8;
;       *(uint4*)(o + tl_off(row, c, DM >> 6)) =
;           make_uint4(pack2(v0.x, v0.y), pack2(v0.z, v0.w), pack2(v1.x, v1.y), pack2(v1.z, v1.w));
;     }
.LBB0_34:
	s_or_b64 exec, exec, s[0:1]
	v_mov_b32_e32 v0, 0
	s_waitcnt lgkmcnt(0)
	s_barrier
	ds_read_b96 v[0:2], v0
	s_cmp_gt_i32 s92, 0
	v_lshl_add_u32 v160, s96, 9, v174
	s_waitcnt lgkmcnt(0)
	v_readfirstlane_b32 s0, v0
	s_nop 1
	v_writelane_b32 v244, s0, 6
	v_readfirstlane_b32 s0, v1
	s_nop 1
	v_writelane_b32 v244, s0, 7
	v_readfirstlane_b32 s0, v2
	s_nop 1
	v_writelane_b32 v244, s0, 8
	s_cselect_b64 s[0:1], -1, 0
	s_cmp_lt_i32 s93, 1
	s_cselect_b64 s[2:3], -1, 0
	s_or_b64 s[0:1], s[0:1], s[2:3]
	s_and_b64 vcc, exec, s[0:1]
	s_cbranch_vccnz .LBB0_121
	v_lshl_add_u32 v4, s96, 9, v174
	s_mov_b32 s3, 0x400000
	s_lshl_b32 s2, s94, 9
	v_cmp_gt_i32_e32 vcc, s3, v4
	s_and_saveexec_b64 s[4:5], vcc
	s_cbranch_execz .LBB0_38
	v_lshlrev_b32_e32 v0, 3, v174
	v_ashrrev_i32_e32 v5, 31, v4
	s_add_u32 s6, s90, 0xa420000
	v_lshl_add_u32 v6, s96, 12, v0
	v_lshlrev_b64 v[0:1], 5, v[4:5]
	s_addc_u32 s7, s91, 0
	v_lshl_add_u64 v[0:1], s[36:37], 0, v[0:1]
	s_ashr_i32 s3, s2, 31
	s_lshl_b32 s28, s94, 12
	v_lshl_add_u64 v[0:1], v[0:1], 0, 16
	s_lshl_b64 s[24:25], s[2:3], 5
	s_mov_b64 s[26:27], 0
	v_mov_b32_e32 v3, 0
	s_mov_b32 s3, 0x3fffff
	v_mov_b32_e32 v5, v4
	s_mul_i32 s98, s2, 3
	s_mov_b64 s[100:101], exec
	v_mov_b32_e32 v71, 0
	v_add_u32_e32 v20, s98, v5
	v_cmp_ge_i32_e32 vcc, s3, v20
	s_and_b64 exec, exec, vcc
	s_cbranch_execz .Lxc_done
.Lxc_loop:
	v_lshl_add_u64 v[22:23], v[0:1], 0, s[24:25]
	v_lshl_add_u64 v[24:25], v[22:23], 0, s[24:25]
	v_lshl_add_u64 v[26:27], v[24:25], 0, s[24:25]
	global_load_dwordx4 v[28:31], v[0:1], off offset:-16
	global_load_dwordx4 v[32:35], v[0:1], off
	global_load_dwordx4 v[36:39], v[22:23], off offset:-16
	global_load_dwordx4 v[40:43], v[22:23], off
	global_load_dwordx4 v[44:47], v[24:25], off offset:-16
	global_load_dwordx4 v[48:51], v[24:25], off
	global_load_dwordx4 v[52:55], v[26:27], off offset:-16
	global_load_dwordx4 v[56:59], v[26:27], off
	v_lshl_add_u64 v[0:1], v[26:27], 0, s[24:25]
	v_ashrrev_i32_e32 v64, 8, v5
	v_ashrrev_i32_e32 v65, 15, v5
	v_bfe_u32 v62, v6, 6, 5
	v_mad_i32_i24 v62, v65, 33, v62
	v_lshrrev_b32_e32 v65, 3, v64
	v_lshrrev_b32_e32 v66, 5, v6
	v_lshlrev_b32_e32 v67, 6, v64
	v_and_b32_e32 v65, 14, v65
	v_lshlrev_b32_e32 v68, 1, v6
	v_lshlrev_b32_e32 v64, 2, v64
	v_ashrrev_i32_e32 v63, 31, v62
	v_and_b32_e32 v67, 0x3c0, v67
	v_and_or_b32 v65, v66, 1, v65
	v_and_b32_e32 v64, 32, v64
	v_lshlrev_b64 v[62:63], 14, v[62:63]
	v_and_or_b32 v66, v68, 48, v67
	v_lshlrev_b32_e32 v65, 10, v65
	v_lshl_add_u64 v[62:63], s[6:7], 0, v[62:63]
	v_bitop3_b32 v70, v66, v65, v64 bitop3:0xde
	v_lshl_add_u64 v[62:63], v[62:63], 0, v[70:71]
	s_waitcnt vmcnt(6)
	v_cvt_pk_bf16_f32 v28, v28, v29
	v_cvt_pk_bf16_f32 v29, v30, v31
	v_cvt_pk_bf16_f32 v30, v32, v33
	v_cvt_pk_bf16_f32 v31, v34, v35
	global_store_dwordx4 v[62:63], v[28:31], off
	v_add_u32_e32 v60, s2, v5
	v_add_u32_e32 v61, s28, v6
	v_ashrrev_i32_e32 v64, 8, v60
	v_ashrrev_i32_e32 v65, 15, v60
	v_bfe_u32 v62, v61, 6, 5
	v_mad_i32_i24 v62, v65, 33, v62
	v_lshrrev_b32_e32 v65, 3, v64
	v_lshrrev_b32_e32 v66, 5, v61
	v_lshlrev_b32_e32 v67, 6, v64
	v_and_b32_e32 v65, 14, v65
	v_lshlrev_b32_e32 v68, 1, v61
	v_lshlrev_b32_e32 v64, 2, v64
	v_ashrrev_i32_e32 v63, 31, v62
	v_and_b32_e32 v67, 0x3c0, v67
	v_and_or_b32 v65, v66, 1, v65
	v_and_b32_e32 v64, 32, v64
	v_lshlrev_b64 v[62:63], 14, v[62:63]
	v_and_or_b32 v66, v68, 48, v67
	v_lshlrev_b32_e32 v65, 10, v65
	v_lshl_add_u64 v[62:63], s[6:7], 0, v[62:63]
	v_bitop3_b32 v70, v66, v65, v64 bitop3:0xde
	v_lshl_add_u64 v[62:63], v[62:63], 0, v[70:71]
	s_waitcnt vmcnt(5)
	v_cvt_pk_bf16_f32 v36, v36, v37
	v_cvt_pk_bf16_f32 v37, v38, v39
	v_cvt_pk_bf16_f32 v38, v40, v41
	v_cvt_pk_bf16_f32 v39, v42, v43
	global_store_dwordx4 v[62:63], v[36:39], off
	v_add_u32_e32 v60, s2, v60
	v_add_u32_e32 v61, s28, v61
	v_ashrrev_i32_e32 v64, 8, v60
	v_ashrrev_i32_e32 v65, 15, v60
	v_bfe_u32 v62, v61, 6, 5
	v_mad_i32_i24 v62, v65, 33, v62
	v_lshrrev_b32_e32 v65, 3, v64
	v_lshrrev_b32_e32 v66, 5, v61
	v_lshlrev_b32_e32 v67, 6, v64
	v_and_b32_e32 v65, 14, v65
	v_lshlrev_b32_e32 v68, 1, v61
	v_lshlrev_b32_e32 v64, 2, v64
	v_ashrrev_i32_e32 v63, 31, v62
	v_and_b32_e32 v67, 0x3c0, v67
	v_and_or_b32 v65, v66, 1, v65
	v_and_b32_e32 v64, 32, v64
	v_lshlrev_b64 v[62:63], 14, v[62:63]
	v_and_or_b32 v66, v68, 48, v67
	v_lshlrev_b32_e32 v65, 10, v65
	v_lshl_add_u64 v[62:63], s[6:7], 0, v[62:63]
	v_bitop3_b32 v70, v66, v65, v64 bitop3:0xde
	v_lshl_add_u64 v[62:63], v[62:63], 0, v[70:71]
	s_waitcnt vmcnt(4)
	v_cvt_pk_bf16_f32 v44, v44, v45
	v_cvt_pk_bf16_f32 v45, v46, v47
	v_cvt_pk_bf16_f32 v46, v48, v49
	v_cvt_pk_bf16_f32 v47, v50, v51
	global_store_dwordx4 v[62:63], v[44:47], off
	v_add_u32_e32 v60, s2, v60
	v_add_u32_e32 v61, s28, v61
	v_ashrrev_i32_e32 v64, 8, v60
	v_ashrrev_i32_e32 v65, 15, v60
	v_bfe_u32 v62, v61, 6, 5
	v_mad_i32_i24 v62, v65, 33, v62
	v_lshrrev_b32_e32 v65, 3, v64
	v_lshrrev_b32_e32 v66, 5, v61
	v_lshlrev_b32_e32 v67, 6, v64
	v_and_b32_e32 v65, 14, v65
	v_lshlrev_b32_e32 v68, 1, v61
	v_lshlrev_b32_e32 v64, 2, v64
	v_ashrrev_i32_e32 v63, 31, v62
	v_and_b32_e32 v67, 0x3c0, v67
	v_and_or_b32 v65, v66, 1, v65
	v_and_b32_e32 v64, 32, v64
	v_lshlrev_b64 v[62:63], 14, v[62:63]
	v_and_or_b32 v66, v68, 48, v67
	v_lshlrev_b32_e32 v65, 10, v65
	v_lshl_add_u64 v[62:63], s[6:7], 0, v[62:63]
	v_bitop3_b32 v70, v66, v65, v64 bitop3:0xde
	v_lshl_add_u64 v[62:63], v[62:63], 0, v[70:71]
	s_waitcnt vmcnt(3)
	v_cvt_pk_bf16_f32 v52, v52, v53
	v_cvt_pk_bf16_f32 v53, v54, v55
	v_cvt_pk_bf16_f32 v54, v56, v57
	v_cvt_pk_bf16_f32 v55, v58, v59
	global_store_dwordx4 v[62:63], v[52:55], off
	v_add_u32_e32 v5, s2, v60
	v_add_u32_e32 v6, s28, v61
	v_add_u32_e32 v20, s98, v5
	v_cmp_ge_i32_e32 vcc, s3, v20
	s_and_b64 exec, exec, vcc
	s_cbranch_execnz .Lxc_loop
.Lxc_done:
	s_mov_b64 exec, s[100:101]
	v_cmp_ge_i32_e32 vcc, s3, v5
	s_and_b64 exec, exec, vcc
	s_cbranch_execz .LBB0_38
